# v41 + K-tile-1 prologue stages issued right after K-tile-0 in all four GEMM phase prologues
# baseline (speedup 1.0000x reference)
.LBB0_84:
	v_readlane_b32 s0, v252, 16
	v_mov_b32_e32 v99, v234
	v_readlane_b32 s1, v252, 17
	s_barrier
	s_andn2_b64 vcc, exec, s[0:1]
	v_readfirstlane_b32 s20, v99
	s_cbranch_vccnz .LBB0_122
	v_lshlrev_b32_e32 v0, 4, v99
	v_add_u32_e32 v1, 0x2000, v0
	v_ashrrev_i32_e32 v2, 31, v1
	v_lshrrev_b32_e32 v2, 22, v2
	v_add_u32_e32 v2, v1, v2
	v_ashrrev_i32_e32 v96, 10, v2
	v_mul_i32_i24_e32 v2, 0x400, v96
	v_sub_u32_e32 v1, v1, v2
	v_lshrrev_b32_e32 v2, 4, v1
	v_bitop3_b32 v1, v2, v1, 32 bitop3:0x6c
	v_ashrrev_i32_e32 v2, 31, v1
	v_lshrrev_b32_e32 v2, 26, v2
	s_ashr_i32 s21, s20, 6
	v_add_u32_e32 v2, v1, v2
	v_lshlrev_b32_e32 v3, 3, v96
	s_lshl_b32 s2, s21, 10
	s_mul_i32 s1, s84, 0x2c00000
	v_readlane_b32 s4, v209, 34
	v_ashrrev_i32_e32 v97, 6, v2
	v_and_b32_e32 v3, -16, v3
	s_mul_hi_i32 s0, s84, 0x2c00000
	v_readlane_b32 s5, v209, 35
	s_add_u32 s3, s4, s1
	v_add_u32_e32 v3, v97, v3
	s_addc_u32 s22, s5, s0
	v_and_b32_e32 v4, 3, v97
	s_mov_b32 s0, 0xfffe0
	v_lshrrev_b32_e32 v5, 2, v3
	v_lshlrev_b32_e32 v6, 1, v3
	v_and_b32_e32 v2, 0xc0, v2
	v_and_or_b32 v4, v3, s0, v4
	v_and_b32_e32 v5, 4, v5
	v_and_b32_e32 v6, 24, v6
	v_sub_u32_e32 v1, v1, v2
	v_or3_b32 v4, v4, v5, v6
	v_lshlrev_b32_e32 v5, 5, v96
	v_ashrrev_i16_sdwa v1, v236, sext(v1) dst_sel:DWORD dst_unused:UNUSED_PAD src0_sel:DWORD src1_sel:BYTE_0
	v_and_b32_e32 v5, 32, v5
	v_bfe_i32 v98, v1, 0, 16
	v_add_lshl_u32 v1, v5, v98, 1
	v_lshl_add_u32 v128, v4, 12, v1
	v_lshl_add_u32 v130, v3, 12, v1
	v_bfe_i32 v1, v99, 27, 1
	v_lshrrev_b32_e32 v1, 22, v1
	v_add_u32_e32 v1, v0, v1
	v_and_b32_e32 v1, 0xfffffc00, v1
	v_sub_u32_e32 v0, v0, v1
	v_lshrrev_b32_e32 v1, 4, v0
	v_bitop3_b32 v1, v1, v0, 32 bitop3:0x6c
	v_ashrrev_i32_e32 v0, 31, v0
	v_lshrrev_b32_e32 v0, 26, v0
	v_add_u32_e32 v0, v1, v0
	v_ashrrev_i32_e32 v100, 6, v0
	v_ashrrev_i32_e32 v0, 31, v99
	v_lshrrev_b32_e32 v0, 26, v0
	v_add_u32_e32 v0, v99, v0
	v_ashrrev_i32_e32 v101, 6, v0
	v_lshlrev_b32_e32 v0, 3, v101
	v_and_b32_e32 v0, -16, v0
	v_add_u32_e32 v0, v100, v0
	v_and_b32_e32 v2, 3, v100
	v_lshrrev_b32_e32 v3, 2, v0
	v_lshlrev_b32_e32 v4, 1, v0
	v_and_or_b32 v2, v0, s0, v2
	v_and_b32_e32 v3, 4, v3
	v_and_b32_e32 v4, 24, v4
	v_or3_b32 v2, v2, v3, v4
	v_mul_i32_i24_e32 v4, 64, v100
	v_sub_u32_e32 v1, v1, v4
	v_lshlrev_b32_e32 v3, 5, v101
	v_ashrrev_i16_sdwa v1, v236, sext(v1) dst_sel:DWORD dst_unused:UNUSED_PAD src0_sel:DWORD src1_sel:BYTE_0
	v_readlane_b32 s0, v253, 43
	v_and_b32_e32 v3, 32, v3
	v_bfe_i32 v102, v1, 0, 16
	v_readlane_b32 s1, v253, 44
	s_add_u32 s0, s3, s0
	v_add_lshl_u32 v1, v3, v102, 1
	s_addc_u32 s1, s22, s1
	s_add_i32 s46, s2, 0
	v_lshl_add_u32 v204, v2, 12, v1
	s_add_i32 m0, s46, 0x10000
	v_lshl_add_u32 v132, v0, 12, v1
	global_load_lds_dwordx4 v204, s[0:1]
	s_add_i32 m0, s46, 0x12000
	s_add_u32 s4, s0, 0x80000
	global_load_lds_dwordx4 v128, s[0:1]
	s_addc_u32 s5, s1, 0
	s_add_i32 m0, s46, 0x14000
	v_mov_b32_e32 v0, v234
	global_load_lds_dwordx4 v204, s[4:5]
	s_add_i32 m0, s46, 0x16000
	v_mov_b32_e32 v1, v205
	global_load_lds_dwordx4 v128, s[4:5]
	v_readlane_b32 s4, v253, 57
	v_readlane_b32 s5, v253, 58
	s_add_u32 s4, s16, s4
	s_addc_u32 s5, s17, s5
	s_add_i32 s47, s46, 0x2000
	s_mov_b32 m0, s46
	s_add_u32 s6, s4, 0x80000
	global_load_lds_dwordx4 v132, s[4:5]
	s_mov_b32 m0, s47
	s_addc_u32 s7, s5, 0
	s_add_i32 s48, s46, 0x4000
	global_load_lds_dwordx4 v130, s[4:5]
	s_mov_b32 m0, s48
	s_add_i32 s49, s46, 0x6000
	global_load_lds_dwordx4 v132, s[6:7]
	s_mov_b32 m0, s49
	v_readlane_b32 s28, v253, 55
	global_load_lds_dwordx4 v130, s[6:7]
	s_add_u32 s26, s0, 0x80080
	s_addc_u32 s27, s1, 0
	s_add_i32 m0, s46, 0x17f80
	s_nop 0
	global_load_lds_dwordx4 v204, s[0:1] offset:128
	s_add_i32 m0, s46, 0x19f80
	s_nop 0
	global_load_lds_dwordx4 v128, s[0:1] offset:128
	s_add_i32 m0, s46, 0x7f80
	s_nop 0
	global_load_lds_dwordx4 v132, s[4:5] offset:128
	s_add_i32 m0, s46, 0x9f80
	s_nop 0
	global_load_lds_dwordx4 v130, s[4:5] offset:128
	s_add_i32 m0, s46, 0x1c000
	s_nop 0
	global_load_lds_dwordx4 v204, s[26:27]
	s_add_i32 m0, s46, 0x1e000
	s_nop 0
	global_load_lds_dwordx4 v128, s[26:27]
	v_readlane_b32 s6, v253, 18
	v_ashrrev_i32_e32 v104, 1, v0
	v_and_b32_e32 v105, 1, v0
	v_add_u32_e32 v2, s6, v104
	v_lshlrev_b32_e32 v0, 6, v105
	v_ashrrev_i32_e32 v3, 31, v2
	v_lshl_add_u64 v[0:1], s[14:15], 0, v[0:1]
	v_lshlrev_b64 v[2:3], 7, v[2:3]
	v_lshl_add_u64 v[2:3], v[0:1], 0, v[2:3]
	global_load_dwordx4 v[60:63], v[2:3], off offset:48
	global_load_dwordx4 v[72:75], v[2:3], off offset:32
	global_load_dwordx4 v[84:87], v[2:3], off offset:16
	global_load_dwordx4 v[92:95], v[2:3], off
	v_readlane_b32 s6, v254, 40
	v_readlane_b32 s7, v254, 41
	s_andn2_b64 vcc, exec, s[6:7]
	s_mov_b32 s6, s28
	v_readlane_b32 s29, v253, 56
	s_cbranch_vccnz .LBB0_87
	v_readlane_b32 s6, v254, 5

.LBB0_109:
	v_lshrrev_b32_e32 v9, 1, v99
	v_and_b32_e32 v9, 24, v9
	v_and_b32_e32 v8, 15, v99
	v_lshlrev_b32_e32 v10, 1, v9
	v_lshl_or_b32 v150, s25, 6, v8
	v_lshl_or_b32 v10, v8, 6, v10
	v_lshlrev_b32_e32 v8, 2, v8
	s_lshl_b32 s21, s21, 5
	s_lshl_b32 s25, s25, 13
	v_and_b32_e32 v11, 32, v8
	s_and_b32 s21, s21, 0x60
	s_add_i32 m0, s46, 0x18000
	v_lshl_add_u64 v[2:3], v[2:3], 0, s[12:13]
	v_bitop3_b32 v12, v10, s25, v11 bitop3:0xde
	s_lshl_b32 s25, s21, 7
	s_waitcnt vmcnt(8)
	s_barrier
	v_lshl_add_u64 v[2:3], v[4:5], 0, s[12:13]
	s_add_i32 m0, s46, 0x1a000
	s_add_i32 s50, s46, 0x8000
	s_add_i32 s51, s46, 0xa000
	v_lshl_add_u64 v[0:1], v[0:1], 0, s[12:13]
	s_mov_b32 m0, s50
	s_add_u32 s26, s0, 0x80080
	v_lshl_add_u64 v[0:1], v[6:7], 0, s[12:13]
	s_mov_b32 m0, s51
	s_addc_u32 s27, s1, 0
	s_add_i32 m0, s46, 0x1c000
	v_lshl_add_u64 v[0:1], s[26:27], 0, v[204:205]
	v_lshl_add_u64 v[0:1], s[26:27], 0, v[128:129]
	s_add_i32 m0, s46, 0x1e000
	s_cmpk_lt_u32 s20, 0x100
	v_lshlrev_b32_e32 v0, 15, v101
	v_and_b32_e32 v0, 0xffff0000, v0
	v_lshl_add_u32 v0, v100, 12, v0
	v_and_b32_e32 v1, 1, v101
	v_lshl_or_b32 v0, v1, 6, v0
	v_lshl_add_u32 v134, v102, 1, v0
	v_lshlrev_b32_e32 v0, 15, v96
	v_and_b32_e32 v0, 0xffff0000, v0
	s_cselect_b64 s[26:27], -1, 0
	s_and_b32 s20, s20, 0xffffff00
	v_lshl_add_u32 v0, v97, 12, v0
	v_and_b32_e32 v1, 1, v96
	s_waitcnt vmcnt(6)
	s_add_i32 s20, s20, 0
	v_lshl_or_b32 v0, v1, 6, v0
	s_add_i32 s20, s20, 0x20000
	v_lshl_add_u32 v136, v98, 1, v0
	v_bitop3_b32 v151, v10, s25, v11 bitop3:0xde
	v_add_u32_e32 v152, s20, v8
	v_or_b32_e32 v153, s21, v9
	v_mov_b32_e32 v135, v205
	v_mov_b32_e32 v137, v205
	s_mov_b32 s53, 0
	v_add_u32_e32 v154, 0, v12
	v_readlane_b32 s52, v253, 19
	s_mov_b32 s54, s28
	s_mov_b32 s56, 0
	s_barrier
	s_branch .LBB0_111

.LBB0_166:
	v_readlane_b32 s0, v252, 26
	v_mov_b32_e32 v12, v234
	v_readlane_b32 s1, v252, 27
	s_andn2_b64 vcc, exec, s[0:1]
	v_readfirstlane_b32 s4, v12
	s_cbranch_vccnz .LBB0_232
	v_lshlrev_b32_e32 v0, 4, v12
	v_add_u32_e32 v1, 0x2000, v0
	v_ashrrev_i32_e32 v2, 31, v1
	v_lshrrev_b32_e32 v2, 22, v2
	v_add_u32_e32 v2, v1, v2
	v_ashrrev_i32_e32 v2, 10, v2
	v_mul_i32_i24_e32 v3, 0x400, v2
	v_sub_u32_e32 v1, v1, v3
	v_lshrrev_b32_e32 v3, 4, v1
	v_bitop3_b32 v1, v3, v1, 32 bitop3:0x6c
	v_ashrrev_i32_e32 v3, 31, v1
	v_lshrrev_b32_e32 v3, 26, v3
	v_add_u32_e32 v3, v1, v3
	v_lshlrev_b32_e32 v5, 3, v2
	v_ashrrev_i32_e32 v4, 6, v3
	v_and_b32_e32 v5, -16, v5
	v_lshlrev_b32_e32 v2, 5, v2
	v_add_u32_e32 v5, v4, v5
	v_and_b32_e32 v13, 32, v2
	v_and_b32_e32 v2, 0xc0, v3
	v_and_b32_e32 v4, 3, v4
	s_mov_b32 s0, 0x7fffffe0
	v_lshrrev_b32_e32 v6, 2, v5
	v_lshlrev_b32_e32 v7, 1, v5
	v_sub_u32_e32 v1, v1, v2
	v_and_or_b32 v4, v5, s0, v4
	v_and_b32_e32 v6, 4, v6
	v_and_b32_e32 v7, 24, v7
	v_ashrrev_i16_sdwa v1, v236, sext(v1) dst_sel:DWORD dst_unused:UNUSED_PAD src0_sel:DWORD src1_sel:BYTE_0
	v_or3_b32 v4, v4, v6, v7
	v_bfe_i32 v14, v1, 0, 16
	v_mul_lo_u32 v4, v4, s20
	v_add_u32_e32 v1, v13, v14
	v_mul_lo_u32 v15, v5, s20
	v_add_lshl_u32 v210, v4, v1, 1
	v_add_lshl_u32 v212, v1, v15, 1
	v_bfe_i32 v1, v12, 27, 1
	v_lshrrev_b32_e32 v1, 22, v1
	v_add_u32_e32 v1, v0, v1
	v_and_b32_e32 v1, 0xfffffc00, v1
	v_sub_u32_e32 v0, v0, v1
	v_ashrrev_i32_e32 v2, 31, v12
	v_lshrrev_b32_e32 v1, 4, v0
	v_lshrrev_b32_e32 v2, 26, v2
	v_bitop3_b32 v1, v1, v0, 32 bitop3:0x6c
	v_ashrrev_i32_e32 v0, 31, v0
	v_add_u32_e32 v2, v12, v2
	v_lshrrev_b32_e32 v0, 26, v0
	v_ashrrev_i32_e32 v2, 6, v2
	v_add_u32_e32 v0, v1, v0
	v_lshlrev_b32_e32 v3, 3, v2
	v_ashrrev_i32_e32 v0, 6, v0
	v_and_b32_e32 v3, -16, v3
	s_lshl_b32 s10, s20, 8
	s_mov_b32 s11, s23
	v_add_u32_e32 v3, v0, v3
	v_and_b32_e32 v4, 3, v0
	s_lshl_b64 s[34:35], s[10:11], 1
	v_and_or_b32 v4, v3, s0, v4
	v_readlane_b32 s0, v253, 54
	v_readlane_b32 s25, v253, 53
	s_mul_i32 s0, s34, s0
	s_mul_hi_u32 s1, s34, s25
	s_add_i32 s0, s1, s0
	s_bfe_u32 s1, s20, 0x10017
	v_readlane_b32 s28, v253, 49
	s_mul_i32 s3, s1, s25
	v_readlane_b32 s29, v253, 50
	v_mul_i32_i24_e32 v0, 64, v0
	s_add_i32 s22, s0, s3
	s_mul_i32 s0, s34, s29
	s_mul_hi_u32 s3, s34, s28
	s_ashr_i32 s21, s4, 6
	v_lshrrev_b32_e32 v5, 2, v3
	v_lshlrev_b32_e32 v6, 1, v3
	v_sub_u32_e32 v0, v1, v0
	s_add_i32 s0, s3, s0
	s_mul_i32 s1, s1, s28
	s_ashr_i32 s5, s4, 8
	s_lshl_b32 s2, s21, 10
	v_and_b32_e32 v5, 4, v5
	v_and_b32_e32 v6, 24, v6
	v_lshlrev_b32_e32 v2, 5, v2
	v_ashrrev_i16_sdwa v0, v236, sext(v0) dst_sel:DWORD dst_unused:UNUSED_PAD src0_sel:DWORD src1_sel:BYTE_0
	s_add_i32 s0, s0, s1
	s_mul_i32 s1, s34, s28
	v_readlane_b32 s28, v209, 43
	v_or3_b32 v4, v4, v5, v6
	v_and_b32_e32 v16, 32, v2
	v_bfe_i32 v17, v0, 0, 16
	v_readlane_b32 s29, v209, 44
	s_add_u32 s36, s28, s1
	v_mul_lo_u32 v4, v4, s20
	v_add_u32_e32 v0, v16, v17
	s_addc_u32 s37, s29, s0
	s_add_i32 s3, s2, 0
	v_add_lshl_u32 v204, v4, v0, 1
	s_add_i32 m0, s3, 0x10000
	v_mov_b32_e32 v211, v205
	global_load_lds_dwordx4 v204, s[36:37]
	s_add_i32 m0, s3, 0x12000
	s_add_u32 s0, s36, s10
	global_load_lds_dwordx4 v210, s[36:37]
	s_addc_u32 s1, s37, 0
	s_add_i32 m0, s3, 0x14000
	s_mul_i32 s25, s34, s25
	global_load_lds_dwordx4 v204, s[0:1]
	s_add_i32 m0, s3, 0x16000
	v_lshl_add_u64 v[4:5], s[0:1], 0, v[204:205]
	v_lshl_add_u64 v[6:7], s[0:1], 0, v[210:211]
	global_load_lds_dwordx4 v210, s[0:1]
	v_readlane_b32 s0, v209, 45
	v_readlane_b32 s1, v209, 46
	s_add_u32 s0, s0, s25
	v_mul_lo_u32 v18, v3, s20
	s_addc_u32 s1, s1, s22
	s_add_i32 s52, s3, 0x2000
	v_add_lshl_u32 v214, v0, v18, 1
	s_mov_b32 m0, s3
	s_add_u32 s28, s0, s10
	global_load_lds_dwordx4 v214, s[0:1]
	s_mov_b32 m0, s52
	s_addc_u32 s29, s1, 0
	s_add_i32 s53, s3, 0x4000
	global_load_lds_dwordx4 v212, s[0:1]
	s_mov_b32 m0, s53
	s_add_i32 s54, s3, 0x6000
	global_load_lds_dwordx4 v214, s[28:29]
	s_mov_b32 m0, s54
	v_mov_b32_e32 v215, v205
	global_load_lds_dwordx4 v212, s[28:29]
	s_add_i32 m0, s3, 0x17f80
	s_nop 0
	global_load_lds_dwordx4 v204, s[36:37] offset:128
	s_add_i32 m0, s3, 0x19f80
	s_nop 0
	global_load_lds_dwordx4 v210, s[36:37] offset:128
	s_add_i32 m0, s3, 0x7f80
	s_nop 0
	global_load_lds_dwordx4 v214, s[0:1] offset:128
	s_add_i32 m0, s3, 0x9f80
	s_nop 0
	global_load_lds_dwordx4 v212, s[0:1] offset:128
	s_add_i32 m0, s3, 0x1bf80
	s_nop 0
	global_load_lds_dwordx4 v[4:5], off offset:128
	s_add_i32 m0, s3, 0x1df80
	s_nop 0
	global_load_lds_dwordx4 v[6:7], off offset:128
	v_mov_b32_e32 v213, v205
	s_cmp_eq_u32 s5, 1
	v_mov_b64_e32 v[202:203], 0x580
	v_mov_b32_e32 v200, v239
	v_mov_b32_e32 v239, v240
	v_mov_b32_e32 v240, v241
	v_mov_b32_e32 v242, 1
	v_lshl_add_u64 v[0:1], s[36:37], 0, v[204:205]
	v_lshl_add_u64 v[2:3], s[36:37], 0, v[210:211]
	v_lshl_add_u64 v[8:9], s[0:1], 0, v[214:215]
	v_lshl_add_u64 v[10:11], s[0:1], 0, v[212:213]
	s_cselect_b64 s[38:39], -1, 0
	s_cmp_lg_u32 s5, 1
	s_cbranch_scc1 .LBB0_169
	s_barrier
.LBB0_169:
	s_add_i32 m0, s3, 0x18000
	v_lshl_add_u64 v[0:1], v[0:1], 0, s[12:13]
	s_waitcnt vmcnt(8)
	s_barrier
	v_lshl_add_u64 v[0:1], v[2:3], 0, s[12:13]
	s_add_i32 m0, s3, 0x1a000
	s_add_i32 s55, s3, 0x8000
	v_lshl_add_u64 v[0:1], v[8:9], 0, s[12:13]
	s_mov_b32 m0, s55
	s_add_i32 s56, s3, 0xa000
	v_lshl_add_u64 v[0:1], v[10:11], 0, s[12:13]
	s_mov_b32 m0, s56
	s_and_b32 s57, s21, 3
	s_add_i32 m0, s3, 0x1c000
	v_lshl_add_u64 v[0:1], v[4:5], 0, s[12:13]
	v_lshl_add_u64 v[0:1], v[6:7], 0, s[12:13]
	s_add_i32 m0, s3, 0x1e000
	s_lshr_b32 s62, s20, 6
	v_bfe_u32 v1, v12, 4, 2
	v_and_b32_e32 v0, 15, v12
	v_lshlrev_b32_e32 v3, 4, v1
	v_lshl_or_b32 v248, s5, 6, v0
	v_lshl_or_b32 v0, v0, 6, v3
	v_lshlrev_b32_e32 v3, 2, v12
	s_lshl_b32 s5, s5, 13
	v_and_b32_e32 v3, 32, v3
	v_bitop3_b32 v4, v0, s5, v3 bitop3:0xde
	s_lshl_b32 s5, s57, 12
	v_bitop3_b32 v249, v0, s5, v3 bitop3:0xde
	s_add_i32 s63, s62, -2
	v_add_u32_e32 v0, v18, v16
	v_lshlrev_b32_e32 v2, 3, v1
	s_cmpk_lt_u32 s4, 0x100
	v_cmp_eq_u32_e64 s[42:43], 0, v1
	v_add_lshl_u32 v0, v0, v17, 1
	v_mov_b32_e32 v1, v205
	s_waitcnt vmcnt(6)
	s_cselect_b64 s[40:41], -1, 0
	s_cmp_lg_u64 s[8:9], 0
	v_lshl_add_u64 v[216:217], s[10:11], 0, v[0:1]
	v_add_u32_e32 v0, v15, v13
	s_cselect_b64 s[44:45], -1, 0
	s_waitcnt lgkmcnt(0)
	s_cmp_lg_u64 s[6:7], 0
	v_add_lshl_u32 v0, v0, v14, 1
	v_lshl_or_b32 v250, s57, 5, v2
	s_mov_b32 s64, 0
	s_cselect_b64 s[46:47], -1, 0
	v_lshl_add_u64 v[218:219], s[10:11], 0, v[0:1]
	v_add_u32_e32 v251, 0, v4
	v_readlane_b32 s66, v253, 48
	v_readlane_b32 s20, v253, 53
	s_barrier
	s_branch .LBB0_172

.LBB0_288:
	s_andn2_b64 vcc, exec, s[0:1]
	s_cbranch_vccnz .LBB0_326
	v_ashrrev_i32_e32 v2, 31, v98
	v_lshrrev_b32_e32 v2, 26, v2
	v_add_u32_e32 v2, v98, v2
	v_ashrrev_i32_e32 v99, 6, v2
	v_bfe_i32 v2, v98, 27, 1
	v_lshlrev_b32_e32 v1, 4, v98
	v_lshrrev_b32_e32 v2, 22, v2
	v_add_u32_e32 v2, v1, v2
	v_and_b32_e32 v2, 0xfffffc00, v2
	v_sub_u32_e32 v2, v1, v2
	v_lshrrev_b32_e32 v3, 4, v2
	v_bitop3_b32 v3, v3, v2, 32 bitop3:0x6c
	v_ashrrev_i32_e32 v2, 31, v2
	v_lshrrev_b32_e32 v2, 26, v2
	v_add_u32_e32 v2, v3, v2
	v_ashrrev_i32_e32 v100, 6, v2
	v_lshlrev_b32_e32 v4, 3, v99
	v_mul_i32_i24_e32 v5, 64, v100
	v_and_b32_e32 v4, -16, v4
	v_sub_u32_e32 v3, v3, v5
	v_add_u32_e32 v2, v100, v4
	v_lshlrev_b32_e32 v4, 5, v99
	v_ashrrev_i16_sdwa v3, v236, sext(v3) dst_sel:DWORD dst_unused:UNUSED_PAD src0_sel:DWORD src1_sel:BYTE_0
	v_and_b32_e32 v4, 32, v4
	v_bfe_i32 v101, v3, 0, 16
	v_and_b32_e32 v6, 3, v100
	s_mov_b32 s0, 0xfffe0
	v_add_lshl_u32 v4, v4, v101, 1
	v_add_u32_e32 v1, 0x2000, v1
	v_lshlrev_b32_e32 v3, 1, v2
	v_lshrrev_b32_e32 v5, 2, v2
	v_and_or_b32 v6, v2, s0, v6
	v_lshl_add_u32 v144, v2, 12, v4
	v_ashrrev_i32_e32 v2, 31, v1
	v_lshrrev_b32_e32 v2, 22, v2
	v_add_u32_e32 v2, v1, v2
	v_ashrrev_i32_e32 v102, 10, v2
	v_mul_i32_i24_e32 v2, 0x400, v102
	v_sub_u32_e32 v1, v1, v2
	v_and_b32_e32 v3, 24, v3
	v_and_b32_e32 v5, 4, v5
	v_lshrrev_b32_e32 v2, 4, v1
	v_or3_b32 v3, v6, v5, v3
	v_bitop3_b32 v1, v2, v1, 32 bitop3:0x6c
	v_lshl_add_u32 v204, v3, 12, v4
	v_ashrrev_i32_e32 v3, 31, v1
	v_lshrrev_b32_e32 v3, 26, v3
	v_lshlrev_b32_e32 v2, 3, v102
	v_add_u32_e32 v3, v1, v3
	v_and_b32_e32 v2, -16, v2
	v_ashrrev_i32_e32 v103, 6, v3
	s_ashr_i32 s34, s25, 6
	v_add_u32_e32 v2, v103, v2
	v_and_b32_e32 v5, 3, v103
	s_lshl_b32 s29, s34, 10
	v_and_or_b32 v5, v2, s0, v5
	s_and_b64 s[0:1], s[2:3], exec
	s_mov_b32 s0, 0x14600000
	s_cselect_b32 s0, 0x13c00000, s0
	s_add_u32 s46, s18, s0
	v_and_b32_e32 v3, 0xc0, v3
	s_addc_u32 s47, s19, 0
	s_ashr_i32 s9, s8, 31
	s_waitcnt lgkmcnt(0)
	s_ashr_i32 s7, s6, 31
	v_sub_u32_e32 v1, v1, v3
	s_or_b32 s48, s28, 1
	s_lshl_b64 s[2:3], s[8:9], 20
	s_lshl_b64 s[0:1], s[6:7], 20
	v_ashrrev_i16_sdwa v1, v236, sext(v1) dst_sel:DWORD dst_unused:UNUSED_PAD src0_sel:DWORD src1_sel:BYTE_0
	s_add_u32 s0, s46, s0
	v_lshlrev_b32_e32 v4, 5, v102
	v_bfe_i32 v104, v1, 0, 16
	v_lshlrev_b32_e32 v1, 1, v2
	v_lshrrev_b32_e32 v3, 2, v2
	s_addc_u32 s1, s47, s1
	s_add_i32 s7, s29, 0
	v_and_b32_e32 v4, 32, v4
	v_and_b32_e32 v1, 24, v1
	v_and_b32_e32 v3, 4, v3
	s_add_i32 m0, s7, 0x10000
	v_or3_b32 v1, v5, v3, v1
	v_add_lshl_u32 v3, v4, v104, 1
	global_load_lds_dwordx4 v204, s[0:1]
	s_add_i32 m0, s7, 0x12000
	v_lshl_add_u32 v148, v1, 12, v3
	s_add_u32 s10, s0, 0x80000
	global_load_lds_dwordx4 v148, s[0:1]
	s_addc_u32 s11, s1, 0
	s_add_i32 m0, s7, 0x14000
	v_lshl_add_u32 v146, v2, 12, v3
	global_load_lds_dwordx4 v204, s[10:11]
	s_add_i32 m0, s7, 0x16000
	s_add_u32 s2, s16, s2
	s_addc_u32 s3, s17, s3
	s_add_i32 s9, s7, 0x2000
	global_load_lds_dwordx4 v148, s[10:11]
	s_mov_b32 m0, s7
	s_add_u32 s10, s2, 0x80000
	global_load_lds_dwordx4 v144, s[2:3]
	s_mov_b32 m0, s9
	s_addc_u32 s11, s3, 0
	s_add_i32 s49, s7, 0x4000
	global_load_lds_dwordx4 v146, s[2:3]
	s_mov_b32 m0, s49
	s_add_i32 s50, s7, 0x6000
	v_mul_f32_e32 v0, 0x4f7ffffe, v0
	global_load_lds_dwordx4 v144, s[10:11]
	s_mov_b32 m0, s50
	v_cvt_u32_f32_e32 v0, v0
	global_load_lds_dwordx4 v146, s[10:11]
	s_add_u32 s10, s0, 0x80080
	s_addc_u32 s11, s1, 0
	s_add_i32 m0, s7, 0x17f80
	s_nop 0
	global_load_lds_dwordx4 v204, s[0:1] offset:128
	s_add_i32 m0, s7, 0x19f80
	s_nop 0
	global_load_lds_dwordx4 v148, s[0:1] offset:128
	s_add_i32 m0, s7, 0x7f80
	s_nop 0
	global_load_lds_dwordx4 v144, s[2:3] offset:128
	s_add_i32 m0, s7, 0x9f80
	s_nop 0
	global_load_lds_dwordx4 v146, s[2:3] offset:128
	s_add_i32 m0, s7, 0x1c000
	s_nop 0
	global_load_lds_dwordx4 v204, s[10:11]
	s_add_i32 m0, s7, 0x1e000
	s_nop 0
	global_load_lds_dwordx4 v148, s[10:11]
	v_readlane_b32 s10, v253, 16
	v_readlane_b32 s11, v253, 17
	s_and_b64 s[10:11], s[10:11], exec
	s_cselect_b32 s10, s48, s28
	v_readlane_b32 s11, v253, 51
	s_sub_i32 s36, 0, s28
	v_readfirstlane_b32 s51, v0
	s_mul_i32 s10, s10, s11
	v_readlane_b32 s11, v253, 41
	s_mul_i32 s36, s36, s51
	s_add_i32 s10, s10, s11
	s_mul_hi_u32 s36, s51, s36
	s_abs_i32 s35, s10
	s_add_i32 s51, s51, s36
	s_mul_hi_u32 s36, s35, s51
	s_mul_i32 s37, s36, s28
	s_sub_i32 s35, s35, s37
	s_ashr_i32 s11, s10, 31
	s_add_i32 s37, s36, 1
	s_sub_i32 s38, s35, s28
	s_cmp_ge_u32 s35, s28
	s_cselect_b32 s36, s37, s36
	s_cselect_b32 s35, s38, s35
	s_add_i32 s37, s36, 1
	s_cmp_ge_u32 s35, s28
	s_cselect_b32 s35, s37, s36
	s_xor_b32 s35, s35, s11
	s_sub_i32 s11, s35, s11
	s_lshl_b32 s35, s11, 2
	s_sub_i32 s36, 32, s35
	s_min_i32 s36, s36, 4
	s_abs_i32 s36, s36
	v_cvt_f32_u32_e32 v0, s36
	s_sub_i32 s37, 0, s36
	s_mul_i32 s11, s11, s28
	s_sub_i32 s10, s10, s11
	v_rcp_iflag_f32_e32 v0, v0
	s_ashr_i32 s11, s10, 31
	s_abs_i32 s10, s10
	v_mov_b32_e32 v1, v234
	v_mul_f32_e32 v0, 0x4f7ffffe, v0
	v_cvt_u32_f32_e32 v0, v0
	s_nop 0
	v_and_b32_e32 v106, 1, v1
	v_readfirstlane_b32 s38, v0
	s_mul_i32 s37, s37, s38
	s_mul_hi_u32 s37, s38, s37
	s_add_i32 s38, s38, s37
	s_mul_hi_u32 s37, s10, s38
	s_mul_i32 s37, s37, s36
	s_sub_i32 s10, s10, s37
	s_sub_i32 s37, s10, s36
	s_cmp_ge_u32 s10, s36
	s_cselect_b32 s10, s37, s10
	s_sub_i32 s37, s10, s36
	s_cmp_ge_u32 s10, s36
	s_cselect_b32 s10, s37, s10
	s_xor_b32 s10, s10, s11
	s_sub_i32 s10, s10, s11
	v_ashrrev_i32_e32 v105, 1, v1
	s_add_i32 s10, s10, s35
	v_lshlrev_b32_e32 v0, 6, v106
	v_mov_b32_e32 v1, v205
	v_lshl_add_u64 v[96:97], s[14:15], 0, v[0:1]
	v_lshl_add_u32 v0, s10, 8, v105
	v_ashrrev_i32_e32 v1, 31, v0
	v_lshlrev_b64 v[0:1], 7, v[0:1]
	v_lshl_add_u64 v[0:1], v[96:97], 0, v[0:1]
	global_load_dwordx4 v[28:31], v[0:1], off
	global_load_dwordx4 v[24:27], v[0:1], off offset:16
	global_load_dwordx4 v[20:23], v[0:1], off offset:32
	global_load_dwordx4 v[16:19], v[0:1], off offset:48
	v_readlane_b32 s10, v254, 50
	v_mov_b64_e32 v[0:1], s[22:23]
	v_readlane_b32 s11, v254, 51
	s_waitcnt vmcnt(0)
	v_mov_b32_e32 v14, v30
	v_mov_b32_e32 v15, v31
	v_mov_b32_e32 v10, v26
	v_mov_b32_e32 v11, v27
	v_mov_b32_e32 v6, v22
	v_mov_b32_e32 v7, v23
	v_mov_b32_e32 v2, v18
	v_mov_b32_e32 v3, v19
	v_cmp_ge_i64_e32 vcc, s[10:11], v[0:1]
	v_mov_b32_e32 v12, v28
	v_mov_b32_e32 v13, v29
	v_mov_b32_e32 v8, v24
	v_mov_b32_e32 v9, v25
	v_mov_b32_e32 v4, v20
	v_mov_b32_e32 v5, v21
	v_mov_b32_e32 v0, v16
	v_mov_b32_e32 v1, v17
	v_mov_b64_e32 v[34:35], v[2:3]
	v_mov_b64_e32 v[38:39], v[6:7]
	v_mov_b64_e32 v[42:43], v[10:11]
	v_mov_b64_e32 v[46:47], v[14:15]
	s_and_b64 vcc, exec, vcc
	v_mov_b64_e32 v[32:33], v[0:1]
	v_mov_b64_e32 v[36:37], v[4:5]
	v_mov_b64_e32 v[40:41], v[8:9]
	v_mov_b64_e32 v[44:45], v[12:13]
	s_cbranch_vccnz .LBB0_291
	v_readlane_b32 s10, v253, 28
	v_readlane_b32 s11, v253, 29
	s_and_b64 s[10:11], s[10:11], exec
	s_cselect_b32 s10, s48, s28
	v_readlane_b32 s11, v253, 30
	s_mul_i32 s10, s10, s11
	v_readlane_b32 s11, v253, 36
	s_add_i32 s10, s10, s11
	s_abs_i32 s35, s10
	s_mul_hi_u32 s36, s35, s51
	s_mul_i32 s37, s36, s28
	s_sub_i32 s35, s35, s37
	s_ashr_i32 s11, s10, 31
	s_add_i32 s37, s36, 1
	s_sub_i32 s38, s35, s28
	s_cmp_ge_u32 s35, s28
	s_cselect_b32 s36, s37, s36
	s_cselect_b32 s35, s38, s35
	s_add_i32 s37, s36, 1
	s_cmp_ge_u32 s35, s28
	s_cselect_b32 s35, s37, s36
	s_xor_b32 s35, s35, s11
	s_sub_i32 s11, s35, s11
	s_lshl_b32 s35, s11, 2
	s_sub_i32 s36, 32, s35
	s_min_i32 s36, s36, 4
	s_abs_i32 s36, s36
	v_cvt_f32_u32_e32 v32, s36
	s_sub_i32 s37, 0, s36
	s_mul_i32 s11, s11, s28
	s_sub_i32 s10, s10, s11
	v_rcp_iflag_f32_e32 v32, v32
	s_ashr_i32 s11, s10, 31
	s_abs_i32 s10, s10
	v_mul_f32_e32 v32, 0x4f7ffffe, v32
	v_cvt_u32_f32_e32 v32, v32
	s_nop 0
	v_readfirstlane_b32 s38, v32
	s_mul_i32 s37, s37, s38
	s_mul_hi_u32 s37, s38, s37
	s_add_i32 s38, s38, s37
	s_mul_hi_u32 s37, s10, s38
	s_mul_i32 s37, s37, s36
	s_sub_i32 s10, s10, s37
	s_sub_i32 s37, s10, s36
	s_cmp_ge_u32 s10, s36
	s_cselect_b32 s10, s37, s10
	s_sub_i32 s37, s10, s36
	s_cmp_ge_u32 s10, s36
	s_cselect_b32 s10, s37, s10
	s_xor_b32 s10, s10, s11
	s_sub_i32 s10, s10, s11
	s_add_i32 s10, s10, s35
	v_lshl_add_u32 v32, s10, 8, v105
	v_ashrrev_i32_e32 v33, 31, v32
	v_lshlrev_b64 v[32:33], 7, v[32:33]
	v_lshl_add_u64 v[44:45], v[96:97], 0, v[32:33]
	global_load_dwordx4 v[32:35], v[44:45], off offset:48
	global_load_dwordx4 v[36:39], v[44:45], off offset:32
	global_load_dwordx4 v[40:43], v[44:45], off offset:16
	s_nop 0
	global_load_dwordx4 v[44:47], v[44:45], off

.LBB0_313:
	v_readlane_b32 s36, v209, 51
	v_lshrrev_b32_e32 v9, 1, v98
	v_readlane_b32 s37, v209, 52
	v_and_b32_e32 v9, 24, v9
	s_lshl_b64 s[36:37], s[36:37], 2
	v_and_b32_e32 v8, 15, v98
	v_lshlrev_b32_e32 v10, 1, v9
	s_add_u32 s52, s20, s36
	v_lshl_or_b32 v157, s35, 6, v8
	v_lshl_or_b32 v10, v8, 6, v10
	v_lshlrev_b32_e32 v8, 2, v8
	s_addc_u32 s53, s21, s37
	s_lshl_b32 s20, s35, 13
	v_and_b32_e32 v11, 32, v8
	v_bitop3_b32 v12, v10, s20, v11 bitop3:0xde
	s_lshl_b32 s20, s34, 5
	s_and_b32 s34, s20, 0x60
	s_add_i32 m0, s7, 0x18000
	v_lshl_add_u64 v[2:3], v[2:3], 0, s[12:13]
	s_lshl_b32 s20, s34, 7
	s_waitcnt vmcnt(8)
	s_barrier
	v_lshl_add_u64 v[2:3], v[4:5], 0, s[12:13]
	s_add_i32 m0, s7, 0x1a000
	s_add_i32 s54, s7, 0x8000
	s_add_i32 s55, s7, 0xa000
	v_bitop3_b32 v159, v10, s20, v11 bitop3:0xde
	v_lshl_add_u64 v[0:1], v[0:1], 0, s[12:13]
	s_mov_b32 m0, s54
	s_add_u32 s20, s0, 0x80080
	v_lshl_add_u64 v[0:1], v[6:7], 0, s[12:13]
	s_mov_b32 m0, s55
	s_addc_u32 s21, s1, 0
	s_add_i32 m0, s7, 0x1c000
	v_lshl_add_u64 v[0:1], s[20:21], 0, v[204:205]
	v_lshl_add_u64 v[0:1], s[20:21], 0, v[148:149]
	s_add_i32 m0, s7, 0x1e000
	s_cmpk_lt_u32 s25, 0x100
	v_lshlrev_b32_e32 v0, 15, v99
	v_and_b32_e32 v0, 0xffff0000, v0
	v_lshl_add_u32 v0, v100, 12, v0
	v_and_b32_e32 v1, 1, v99
	v_lshl_or_b32 v0, v1, 6, v0
	v_lshl_add_u32 v150, v101, 1, v0
	v_lshlrev_b32_e32 v0, 15, v102
	v_and_b32_e32 v0, 0xffff0000, v0
	s_cselect_b64 s[20:21], -1, 0
	s_and_b32 s25, s25, 0xffffff00
	v_lshl_add_u32 v0, v103, 12, v0
	v_and_b32_e32 v1, 1, v102
	s_waitcnt vmcnt(6)
	s_add_i32 s25, s25, 0
	v_lshl_or_b32 v0, v1, 6, v0
	s_add_i32 s25, s25, 0x20000
	v_lshl_add_u32 v152, v104, 1, v0
	v_add_u32_e32 v161, s25, v8
	v_or_b32_e32 v163, s34, v9
	v_mov_b32_e32 v151, v205
	v_mov_b32_e32 v153, v205
	s_mov_b32 s56, 0
	v_add_u32_e32 v165, 0, v12
	s_mov_b32 s64, 0
	s_barrier
	s_branch .LBB0_315

.LBB0_327:
	s_and_b64 vcc, exec, s[0:1]
	s_cbranch_vccz .LBB0_402
	v_readlane_b32 s0, v252, 24
	v_mov_b32_e32 v99, v234
	v_readlane_b32 s1, v252, 25
	s_andn2_b64 vcc, exec, s[0:1]
	v_readfirstlane_b32 s8, v99
	s_cbranch_vccnz .LBB0_402
	v_lshlrev_b32_e32 v0, 4, v99
	v_add_u32_e32 v1, 0x2000, v0
	v_ashrrev_i32_e32 v2, 31, v1
	v_lshrrev_b32_e32 v2, 22, v2
	v_add_u32_e32 v2, v1, v2
	v_ashrrev_i32_e32 v96, 10, v2
	v_mul_i32_i24_e32 v2, 0x400, v96
	v_sub_u32_e32 v1, v1, v2
	v_lshrrev_b32_e32 v2, 4, v1
	v_bitop3_b32 v1, v2, v1, 32 bitop3:0x6c
	v_ashrrev_i32_e32 v2, 31, v1
	v_lshrrev_b32_e32 v2, 26, v2
	v_add_u32_e32 v2, v1, v2
	v_lshlrev_b32_e32 v3, 3, v96
	s_waitcnt lgkmcnt(0)
	s_ashr_i32 s6, s8, 6
	v_ashrrev_i32_e32 v97, 6, v2
	v_and_b32_e32 v3, -16, v3
	s_lshl_b32 s38, s6, 10
	s_lshl_b64 s[0:1], s[84:85], 24
	v_readlane_b32 s2, v209, 40
	v_add_u32_e32 v3, v97, v3
	s_add_u32 s39, s2, s0
	v_and_b32_e32 v4, 3, v97
	s_mov_b32 s0, 0xfffe0
	v_lshrrev_b32_e32 v5, 2, v3
	v_lshlrev_b32_e32 v6, 1, v3
	v_and_b32_e32 v2, 0xc0, v2
	v_and_or_b32 v4, v3, s0, v4
	v_and_b32_e32 v5, 4, v5
	v_and_b32_e32 v6, 24, v6
	v_sub_u32_e32 v1, v1, v2
	v_or3_b32 v4, v4, v5, v6
	v_lshlrev_b32_e32 v5, 5, v96
	v_ashrrev_i16_sdwa v1, v236, sext(v1) dst_sel:DWORD dst_unused:UNUSED_PAD src0_sel:DWORD src1_sel:BYTE_0
	v_and_b32_e32 v5, 32, v5
	v_bfe_i32 v98, v1, 0, 16
	v_add_lshl_u32 v1, v5, v98, 1
	v_lshl_add_u32 v128, v4, 12, v1
	v_lshl_add_u32 v130, v3, 12, v1
	v_bfe_i32 v1, v99, 27, 1
	v_lshrrev_b32_e32 v1, 22, v1
	v_add_u32_e32 v1, v0, v1
	v_and_b32_e32 v1, 0xfffffc00, v1
	v_sub_u32_e32 v0, v0, v1
	v_lshrrev_b32_e32 v1, 4, v0
	v_bitop3_b32 v1, v1, v0, 32 bitop3:0x6c
	v_ashrrev_i32_e32 v0, 31, v0
	v_lshrrev_b32_e32 v0, 26, v0
	v_add_u32_e32 v0, v1, v0
	v_ashrrev_i32_e32 v100, 6, v0
	v_ashrrev_i32_e32 v0, 31, v99
	v_lshrrev_b32_e32 v0, 26, v0
	v_add_u32_e32 v0, v99, v0
	v_ashrrev_i32_e32 v101, 6, v0
	v_lshlrev_b32_e32 v0, 3, v101
	v_and_b32_e32 v0, -16, v0
	v_add_u32_e32 v0, v100, v0
	v_and_b32_e32 v2, 3, v100
	v_lshrrev_b32_e32 v3, 2, v0
	v_lshlrev_b32_e32 v4, 1, v0
	v_and_or_b32 v2, v0, s0, v2
	v_and_b32_e32 v3, 4, v3
	v_and_b32_e32 v4, 24, v4
	v_or3_b32 v2, v2, v3, v4
	v_mul_i32_i24_e32 v4, 64, v100
	v_readlane_b32 s3, v209, 41
	v_sub_u32_e32 v1, v1, v4
	s_addc_u32 s40, s3, s1
	v_lshlrev_b32_e32 v3, 5, v101
	v_ashrrev_i16_sdwa v1, v236, sext(v1) dst_sel:DWORD dst_unused:UNUSED_PAD src0_sel:DWORD src1_sel:BYTE_0
	v_readlane_b32 s0, v253, 46
	v_and_b32_e32 v3, 32, v3
	v_bfe_i32 v102, v1, 0, 16
	v_readlane_b32 s1, v253, 47
	s_add_u32 s0, s39, s0
	v_add_lshl_u32 v1, v3, v102, 1
	s_addc_u32 s1, s40, s1
	s_add_i32 s41, s38, 0
	v_lshl_add_u32 v204, v2, 12, v1
	s_add_i32 m0, s41, 0x10000
	v_lshl_add_u32 v132, v0, 12, v1
	global_load_lds_dwordx4 v204, s[0:1]
	s_add_i32 m0, s41, 0x12000
	s_add_u32 s2, s0, 0x80000
	global_load_lds_dwordx4 v128, s[0:1]
	s_addc_u32 s3, s1, 0
	s_add_i32 m0, s41, 0x14000
	v_mov_b32_e32 v0, v234
	global_load_lds_dwordx4 v204, s[2:3]
	s_add_i32 m0, s41, 0x16000
	v_mov_b32_e32 v1, v205
	global_load_lds_dwordx4 v128, s[2:3]
	v_readlane_b32 s2, v253, 61
	v_readlane_b32 s3, v253, 62
	s_add_u32 s2, s16, s2
	s_addc_u32 s3, s17, s3
	s_add_i32 s42, s41, 0x2000
	s_mov_b32 m0, s41
	s_add_u32 s4, s2, 0x80000
	global_load_lds_dwordx4 v132, s[2:3]
	s_mov_b32 m0, s42
	s_addc_u32 s5, s3, 0
	s_add_i32 s43, s41, 0x4000
	global_load_lds_dwordx4 v130, s[2:3]
	s_mov_b32 m0, s43
	s_add_i32 s44, s41, 0x6000
	global_load_lds_dwordx4 v132, s[4:5]
	s_mov_b32 m0, s44
	s_nop 0
	global_load_lds_dwordx4 v130, s[4:5]
	s_add_u32 s4, s0, 0x80080
	s_addc_u32 s5, s1, 0
	s_add_i32 m0, s41, 0x17f80
	s_nop 0
	global_load_lds_dwordx4 v204, s[0:1] offset:128
	s_add_i32 m0, s41, 0x19f80
	s_nop 0
	global_load_lds_dwordx4 v128, s[0:1] offset:128
	s_add_i32 m0, s41, 0x7f80
	s_nop 0
	global_load_lds_dwordx4 v132, s[2:3] offset:128
	s_add_i32 m0, s41, 0x9f80
	s_nop 0
	global_load_lds_dwordx4 v130, s[2:3] offset:128
	s_add_i32 m0, s41, 0x1c000
	s_nop 0
	global_load_lds_dwordx4 v204, s[4:5]
	s_add_i32 m0, s41, 0x1e000
	s_nop 0
	global_load_lds_dwordx4 v128, s[4:5]
	v_readlane_b32 s4, v253, 35
	v_ashrrev_i32_e32 v104, 1, v0
	v_and_b32_e32 v105, 1, v0
	v_add_u32_e32 v2, s4, v104
	v_lshlrev_b32_e32 v0, 6, v105
	v_ashrrev_i32_e32 v3, 31, v2
	v_lshl_add_u64 v[0:1], s[14:15], 0, v[0:1]
	v_lshlrev_b64 v[2:3], 7, v[2:3]
	v_lshl_add_u64 v[2:3], v[0:1], 0, v[2:3]
	global_load_dwordx4 v[64:67], v[2:3], off offset:48
	global_load_dwordx4 v[76:79], v[2:3], off offset:32
	global_load_dwordx4 v[84:87], v[2:3], off offset:16
	global_load_dwordx4 v[92:95], v[2:3], off
	v_readlane_b32 s4, v254, 52
	v_readlane_b32 s5, v254, 53
	v_readlane_b32 s14, v253, 59
	s_andn2_b64 vcc, exec, s[4:5]
	s_mov_b32 s4, s14
	v_readlane_b32 s15, v253, 60
	s_cbranch_vccnz .LBB0_331
	v_readlane_b32 s4, v254, 16

.LBB0_353:
	v_bfe_u32 v9, v99, 4, 2
	v_and_b32_e32 v8, 15, v99
	v_lshlrev_b32_e32 v11, 4, v9
	v_lshl_or_b32 v153, s7, 6, v8
	v_lshl_or_b32 v11, v8, 6, v11
	v_lshlrev_b32_e32 v8, 2, v8
	s_and_b32 s45, s6, 3
	s_lshl_b32 s6, s7, 13
	v_and_b32_e32 v12, 32, v8
	s_add_i32 m0, s41, 0x18000
	v_lshl_add_u64 v[2:3], v[2:3], 0, s[12:13]
	v_bitop3_b32 v13, v11, s6, v12 bitop3:0xde
	s_lshl_b32 s6, s45, 12
	s_waitcnt vmcnt(8)
	s_barrier
	v_lshl_add_u64 v[2:3], v[4:5], 0, s[12:13]
	s_add_i32 m0, s41, 0x1a000
	s_add_i32 s46, s41, 0x8000
	s_add_i32 s47, s41, 0xa000
	v_bitop3_b32 v154, v11, s6, v12 bitop3:0xde
	v_lshl_add_u64 v[0:1], v[0:1], 0, s[12:13]
	s_mov_b32 m0, s46
	s_add_u32 s6, s0, 0x80080
	v_lshl_add_u64 v[0:1], v[6:7], 0, s[12:13]
	s_mov_b32 m0, s47
	s_addc_u32 s7, s1, 0
	s_add_i32 m0, s41, 0x1c000
	v_lshl_add_u64 v[0:1], s[6:7], 0, v[204:205]
	v_lshl_add_u64 v[0:1], s[6:7], 0, v[128:129]
	s_add_i32 m0, s41, 0x1e000
	v_cmp_lt_i32_e32 vcc, v243, v238
	s_nop 0
	v_cndmask_b32_e32 v0, v237, v243, vcc
	v_cmp_lt_i32_e32 vcc, v244, v238
	v_lshlrev_b32_e32 v157, 2, v0
	v_and_b32_e32 v1, 1, v101
	v_cndmask_b32_e32 v0, v237, v244, vcc
	v_lshlrev_b32_e32 v158, 2, v0
	v_lshlrev_b32_e32 v0, 15, v101
	v_and_b32_e32 v0, 0xffff0000, v0
	v_lshl_add_u32 v0, v100, 12, v0
	v_lshl_or_b32 v0, v1, 6, v0
	v_lshl_add_u32 v134, v102, 1, v0
	v_lshlrev_b32_e32 v0, 15, v96
	s_cmpk_lt_u32 s8, 0x100
	v_and_b32_e32 v0, 0xffff0000, v0
	s_cselect_b64 s[6:7], -1, 0
	s_and_b32 s8, s8, 0xffffff00
	v_lshl_add_u32 v0, v97, 12, v0
	v_and_b32_e32 v1, 1, v96
	s_waitcnt vmcnt(6)
	s_add_i32 s8, s8, 0
	v_lshl_or_b32 v0, v1, 6, v0
	v_lshlrev_b32_e32 v10, 3, v9
	s_add_i32 s8, s8, 0x20000
	v_lshl_add_u32 v136, v98, 1, v0
	v_lshl_or_b32 v155, s45, 5, v10
	s_mov_b32 s48, 0
	v_cmp_eq_u32_e64 s[60:61], 0, v9
	v_add_u32_e32 v156, s8, v8
	v_mov_b32_e32 v135, v205
	v_mov_b32_e32 v137, v205
	v_add_u32_e32 v159, 0, v13
	v_readlane_b32 s49, v253, 45
	s_mov_b32 s50, s14
	s_mov_b32 s52, 0
	s_barrier
	s_branch .LBB0_355
